# K-loops: the 6 LDS-DMA pieces of phases 2 and 4 issued between the MFMAs of the following cluster instead of before the phase barrier (closing wait vmcnt(2)); on v38
# baseline (speedup 1.0000x reference)
; #define PG8_STAGE(bufoff, gbase, voff) do { _Pragma("unroll") for (int _i = 0; _i < 2; ++_i) \
;         __builtin_amdgcn_global_load_lds((const unsigned*)((const char*)(gbase) + (voff)[_i]), (PG8_LAS unsigned*)(lds + (bufoff) + ldsw + _i * 8192), 16, 0, 0); } while (0)
; #define PG8_LDA(dst, b, h) do { _Pragma("unroll") for (int m = 0; m < 4; ++m) _Pragma("unroll") for (int k = 0; k < 2; ++k) dst[m][k] = *(const PG8_LAS bf16x8*)(lds + PG8_SA(b, h) + aoff + m * 2048 + k * 1024); } while (0)
; #define PG8_MMA(ai, bj, At, Bt) do { __builtin_amdgcn_s_setprio(1); _Pragma("unroll") for (int m = 0; m < 4; ++m) _Pragma("unroll") for (int n = 0; n < 2; ++n) _Pragma("unroll") for (int k = 0; k < 2; ++k) \
;         acc[ai][bj][m][n] = __builtin_amdgcn_mfma_f32_16x16x32_bf16(Bt[n][k], At[m][k], acc[ai][bj][m][n], 0, 0, 0); __builtin_amdgcn_s_setprio(0); } while (0)
; #define PG8_WAIT_V(n) asm volatile("s_waitcnt vmcnt(" #n ")" ::: "memory")
; #define PG8_WAIT_L(n) asm volatile("s_waitcnt lgkmcnt(" #n ")" ::: "memory")
; #define PG8_BAR __builtin_amdgcn_s_barrier()
; #define PG8_SCHED __builtin_amdgcn_sched_barrier(0)
; template <class Epi, class Sched, bool ALIGN_EPI = false, bool SP2 = false>
; __device__ __forceinline__ void gemm_phase(PG8_LAS unsigned char* lds, const Gemm g, const Sched& S, const Epi& E, const int tid) {
;     ...
;             PG8_WAIT_V(8); PG8_WAIT_L(0); PG8_BAR; PG8_MMA(0, 0, At, B0); PG8_MMA(0, 1, At, B1); PG8_BAR; PG8_SCHED;
;             PG8_LDA(At, 0, 1); PG8_STAGE(PG8_SB(0, 0), b2, voffB); PG8_STAGE(PG8_SB(0, 1), b2 + hstepB, voffB); PG8_STAGE(PG8_SA(0, 0), a2, voffA);
;             PG8_WAIT_V(8); PG8_WAIT_L(0); PG8_BAR; PG8_MMA(1, 0, At, B0); PG8_MMA(1, 1, At, B1); PG8_BAR; PG8_SCHED;
.Lkw_up_0:
	s_waitcnt lgkmcnt(0)
	s_barrier
	s_setprio 1
	s_waitcnt lgkmcnt(0)
	v_mfma_f32_16x16x32_bf16 v[124:127], v[148:151], v[208:211], v[124:127]
	v_mfma_f32_16x16x32_bf16 v[120:123], v[162:165], v[208:211], v[120:123]
	v_mfma_f32_16x16x32_bf16 v[108:111], v[148:151], v[216:219], v[108:111]
	v_mfma_f32_16x16x32_bf16 v[104:107], v[162:165], v[216:219], v[104:107]
	v_mfma_f32_16x16x32_bf16 v[92:95], v[148:151], v[224:227], v[92:95]
	v_mfma_f32_16x16x32_bf16 v[88:91], v[162:165], v[224:227], v[88:91]
	v_mfma_f32_16x16x32_bf16 v[76:79], v[148:151], v[232:235], v[76:79]
	v_mfma_f32_16x16x32_bf16 v[72:75], v[162:165], v[232:235], v[72:75]
	v_mfma_f32_16x16x32_bf16 v[124:127], v[158:161], v[212:215], v[124:127]
	v_mfma_f32_16x16x32_bf16 v[120:123], v[188:191], v[212:215], v[120:123]
	v_mfma_f32_16x16x32_bf16 v[108:111], v[158:161], v[220:223], v[108:111]
	v_mfma_f32_16x16x32_bf16 v[104:107], v[188:191], v[220:223], v[104:107]
	v_mfma_f32_16x16x32_bf16 v[92:95], v[158:161], v[228:231], v[92:95]
	v_mfma_f32_16x16x32_bf16 v[88:91], v[188:191], v[228:231], v[88:91]
	v_mfma_f32_16x16x32_bf16 v[76:79], v[158:161], v[236:239], v[76:79]
	v_mfma_f32_16x16x32_bf16 v[72:75], v[188:191], v[236:239], v[72:75]
	s_setprio 0
	s_setprio 1
	v_mfma_f32_16x16x32_bf16 v[116:119], v[192:195], v[208:211], v[116:119]
	v_mfma_f32_16x16x32_bf16 v[112:115], v[200:203], v[208:211], v[112:115]
	v_mfma_f32_16x16x32_bf16 v[100:103], v[192:195], v[216:219], v[100:103]
	v_mfma_f32_16x16x32_bf16 v[96:99], v[200:203], v[216:219], v[96:99]
	v_mfma_f32_16x16x32_bf16 v[84:87], v[192:195], v[224:227], v[84:87]
	v_mfma_f32_16x16x32_bf16 v[80:83], v[200:203], v[224:227], v[80:83]
	v_mfma_f32_16x16x32_bf16 v[68:71], v[192:195], v[232:235], v[68:71]
	v_mfma_f32_16x16x32_bf16 v[64:67], v[200:203], v[232:235], v[64:67]
	v_mfma_f32_16x16x32_bf16 v[116:119], v[196:199], v[212:215], v[116:119]
	v_mfma_f32_16x16x32_bf16 v[112:115], v[204:207], v[212:215], v[112:115]
	v_mfma_f32_16x16x32_bf16 v[100:103], v[196:199], v[220:223], v[100:103]
	v_mfma_f32_16x16x32_bf16 v[96:99], v[204:207], v[220:223], v[96:99]
	v_mfma_f32_16x16x32_bf16 v[84:87], v[196:199], v[228:231], v[84:87]
	v_mfma_f32_16x16x32_bf16 v[80:83], v[204:207], v[228:231], v[80:83]
	v_mfma_f32_16x16x32_bf16 v[68:71], v[196:199], v[236:239], v[68:71]
	v_mfma_f32_16x16x32_bf16 v[64:67], v[204:207], v[236:239], v[64:67]
	s_setprio 0
	s_barrier
	s_add_i32 s36, s36, s68
	v_lshl_add_u64 v[166:167], s[18:19], 0, v[140:141]
	s_mov_b32 m0, s36
	ds_read_b128 v[208:211], v157 offset:16384
	ds_read_b128 v[212:215], v157 offset:17408
	ds_read_b128 v[216:219], v157 offset:18432
	ds_read_b128 v[220:223], v157 offset:19456
	ds_read_b128 v[224:227], v157 offset:20480
	ds_read_b128 v[228:231], v157 offset:21504
	ds_read_b128 v[232:235], v157 offset:22528
	ds_read_b128 v[236:239], v157 offset:23552
	s_cmp_eq_u32 s99, 1
	s_cbranch_scc1 .Lkw_up_1
	s_waitcnt vmcnt(2)
.Lkw_up_1:
	s_waitcnt lgkmcnt(0)
	s_barrier
	s_setprio 1
	s_waitcnt lgkmcnt(0)
	v_mfma_f32_16x16x32_bf16 v[60:63], v[148:151], v[208:211], v[60:63]
	v_mfma_f32_16x16x32_bf16 v[56:59], v[162:165], v[208:211], v[56:59]
	global_load_lds_dwordx4 v[166:167], off
	v_mfma_f32_16x16x32_bf16 v[44:47], v[148:151], v[216:219], v[44:47]
	v_mfma_f32_16x16x32_bf16 v[40:43], v[162:165], v[216:219], v[40:43]
	v_mfma_f32_16x16x32_bf16 v[28:31], v[148:151], v[224:227], v[28:31]
	v_mfma_f32_16x16x32_bf16 v[24:27], v[162:165], v[224:227], v[24:27]
	v_mfma_f32_16x16x32_bf16 v[12:15], v[148:151], v[232:235], v[12:15]
	s_add_i32 m0, s36, 0x2000
	s_add_u32 s36, s18, 0x40000
	v_lshl_add_u64 v[240:241], s[18:19], 0, v[136:137]
	s_addc_u32 s37, s19, 0
	s_add_i32 s38, s38, s68
	global_load_lds_dwordx4 v[240:241], off
	v_mfma_f32_16x16x32_bf16 v[8:11], v[162:165], v[232:235], v[8:11]
	v_mfma_f32_16x16x32_bf16 v[60:63], v[158:161], v[212:215], v[60:63]
	v_mfma_f32_16x16x32_bf16 v[56:59], v[188:191], v[212:215], v[56:59]
	v_mfma_f32_16x16x32_bf16 v[44:47], v[158:161], v[220:223], v[44:47]
	v_mfma_f32_16x16x32_bf16 v[40:43], v[188:191], v[220:223], v[40:43]
	v_lshl_add_u64 v[242:243], s[36:37], 0, v[140:141]
	s_mov_b32 m0, s38
	v_lshl_add_u64 v[244:245], s[22:23], 0, v[138:139]
	global_load_lds_dwordx4 v[242:243], off
	v_mfma_f32_16x16x32_bf16 v[28:31], v[158:161], v[228:231], v[28:31]
	v_mfma_f32_16x16x32_bf16 v[24:27], v[188:191], v[228:231], v[24:27]
	v_mfma_f32_16x16x32_bf16 v[12:15], v[158:161], v[236:239], v[12:15]
	v_mfma_f32_16x16x32_bf16 v[8:11], v[188:191], v[236:239], v[8:11]
	s_setprio 0
	s_setprio 1
	v_mfma_f32_16x16x32_bf16 v[52:55], v[192:195], v[208:211], v[52:55]
	v_lshl_add_u64 v[242:243], s[36:37], 0, v[136:137]
	s_add_i32 m0, s38, 0x2000
	s_nop 0
	global_load_lds_dwordx4 v[242:243], off
	v_mfma_f32_16x16x32_bf16 v[48:51], v[200:203], v[208:211], v[48:51]
	v_mfma_f32_16x16x32_bf16 v[36:39], v[192:195], v[216:219], v[36:39]
	v_mfma_f32_16x16x32_bf16 v[32:35], v[200:203], v[216:219], v[32:35]
	v_mfma_f32_16x16x32_bf16 v[20:23], v[192:195], v[224:227], v[20:23]
	v_mfma_f32_16x16x32_bf16 v[16:19], v[200:203], v[224:227], v[16:19]
	v_lshl_add_u64 v[242:243], s[22:23], 0, v[142:143]
	s_mov_b32 m0, s69
	s_nop 0
	global_load_lds_dwordx4 v[242:243], off
	v_mfma_f32_16x16x32_bf16 v[4:7], v[192:195], v[232:235], v[4:7]
	v_mfma_f32_16x16x32_bf16 v[0:3], v[200:203], v[232:235], v[0:3]
	v_mfma_f32_16x16x32_bf16 v[52:55], v[196:199], v[212:215], v[52:55]
	v_mfma_f32_16x16x32_bf16 v[48:51], v[204:207], v[212:215], v[48:51]
	v_mfma_f32_16x16x32_bf16 v[36:39], v[196:199], v[220:223], v[36:39]
	s_mov_b32 m0, s70
	s_nop 0
	global_load_lds_dwordx4 v[244:245], off
	v_mfma_f32_16x16x32_bf16 v[32:35], v[204:207], v[220:223], v[32:35]
	v_mfma_f32_16x16x32_bf16 v[20:23], v[196:199], v[228:231], v[20:23]
	v_mfma_f32_16x16x32_bf16 v[16:19], v[204:207], v[228:231], v[16:19]
	v_mfma_f32_16x16x32_bf16 v[4:7], v[196:199], v[236:239], v[4:7]
	v_mfma_f32_16x16x32_bf16 v[0:3], v[204:207], v[236:239], v[0:3]
	s_setprio 0
	s_barrier
; #define PG8_STAGE(bufoff, gbase, voff) do { _Pragma("unroll") for (int _i = 0; _i < 2; ++_i) \
;         __builtin_amdgcn_global_load_lds((const unsigned*)((const char*)(gbase) + (voff)[_i]), (PG8_LAS unsigned*)(lds + (bufoff) + ldsw + _i * 8192), 16, 0, 0); } while (0)
; #define PG8_LDA(dst, b, h) do { _Pragma("unroll") for (int m = 0; m < 4; ++m) _Pragma("unroll") for (int k = 0; k < 2; ++k) dst[m][k] = *(const PG8_LAS bf16x8*)(lds + PG8_SA(b, h) + aoff + m * 2048 + k * 1024); } while (0)
; #define PG8_LDB(dst, b, h) do { _Pragma("unroll") for (int n = 0; n < 2; ++n) _Pragma("unroll") for (int k = 0; k < 2; ++k) dst[n][k] = *(const PG8_LAS bf16x8*)(lds + PG8_SB(b, h) + boff + n * 2048 + k * 1024); } while (0)
; #define PG8_MMA(ai, bj, At, Bt) do { __builtin_amdgcn_s_setprio(1); _Pragma("unroll") for (int m = 0; m < 4; ++m) _Pragma("unroll") for (int n = 0; n < 2; ++n) _Pragma("unroll") for (int k = 0; k < 2; ++k) \
;         acc[ai][bj][m][n] = __builtin_amdgcn_mfma_f32_16x16x32_bf16(Bt[n][k], At[m][k], acc[ai][bj][m][n], 0, 0, 0); __builtin_amdgcn_s_setprio(0); } while (0)
; #define PG8_WAIT_V(n) asm volatile("s_waitcnt vmcnt(" #n ")" ::: "memory")
; #define PG8_WAIT_L(n) asm volatile("s_waitcnt lgkmcnt(" #n ")" ::: "memory")
; #define PG8_BAR __builtin_amdgcn_s_barrier()
; #define PG8_SCHED __builtin_amdgcn_sched_barrier(0)
; template <class Epi, class Sched, bool ALIGN_EPI = false, bool SP2 = false>
; __device__ __forceinline__ void gemm_phase(PG8_LAS unsigned char* lds, const Gemm g, const Sched& S, const Epi& E, const int tid) {
;     ...
;             PG8_LDB(B0, 1, 0); PG8_LDB(B1, 1, 1); PG8_SCHED; PG8_LDA(At, 1, 0); PG8_STAGE(PG8_SA(0, 1), a2 + hstepA, voffA);
;             PG8_WAIT_V(8); PG8_WAIT_L(0); PG8_BAR; PG8_MMA(0, 0, At, B0); PG8_MMA(0, 1, At, B1); PG8_BAR; PG8_SCHED;
	s_add_i32 s36, 0, 0x18000
	v_add_u32_e32 v128, s36, v155
	s_add_i32 s37, 0, 0x1c000
	ds_read_b128 v[148:151], v128
	ds_read_b128 v[158:161], v128 offset:1024
	ds_read_b128 v[162:165], v128 offset:2048
	ds_read_b128 v[188:191], v128 offset:3072
	v_add_u32_e32 v128, s37, v155
	ds_read_b128 v[192:195], v128
	ds_read_b128 v[196:199], v128 offset:1024
	ds_read_b128 v[200:203], v128 offset:2048
	ds_read_b128 v[204:207], v128 offset:3072
	s_add_u32 s22, s22, 0x80000
	s_addc_u32 s23, s23, 0
	s_mov_b32 m0, s71
	v_lshl_add_u64 v[246:247], s[22:23], 0, v[142:143]
	ds_read_b128 v[208:211], v157 offset:32768
	ds_read_b128 v[212:215], v157 offset:33792
	ds_read_b128 v[216:219], v157 offset:34816
	ds_read_b128 v[220:223], v157 offset:35840
	ds_read_b128 v[224:227], v157 offset:36864
	ds_read_b128 v[228:231], v157 offset:37888
	ds_read_b128 v[232:235], v157 offset:38912
	ds_read_b128 v[236:239], v157 offset:39936
	global_load_lds_dwordx4 v[246:247], off
	v_lshl_add_u64 v[246:247], s[22:23], 0, v[138:139]
	s_mov_b32 m0, s74
	s_nop 0
	global_load_lds_dwordx4 v[246:247], off
	s_waitcnt vmcnt(8)
	s_waitcnt lgkmcnt(0)
	s_barrier
	s_setprio 1
	s_waitcnt lgkmcnt(0)
	v_mfma_f32_16x16x32_bf16 v[124:127], v[148:151], v[208:211], v[124:127]
	v_mfma_f32_16x16x32_bf16 v[120:123], v[162:165], v[208:211], v[120:123]
	v_mfma_f32_16x16x32_bf16 v[108:111], v[148:151], v[216:219], v[108:111]
	v_mfma_f32_16x16x32_bf16 v[104:107], v[162:165], v[216:219], v[104:107]
	v_mfma_f32_16x16x32_bf16 v[92:95], v[148:151], v[224:227], v[92:95]
	v_mfma_f32_16x16x32_bf16 v[88:91], v[162:165], v[224:227], v[88:91]
	v_mfma_f32_16x16x32_bf16 v[76:79], v[148:151], v[232:235], v[76:79]
	v_mfma_f32_16x16x32_bf16 v[72:75], v[162:165], v[232:235], v[72:75]
	v_mfma_f32_16x16x32_bf16 v[124:127], v[158:161], v[212:215], v[124:127]
	v_mfma_f32_16x16x32_bf16 v[120:123], v[188:191], v[212:215], v[120:123]
	v_mfma_f32_16x16x32_bf16 v[108:111], v[158:161], v[220:223], v[108:111]
	v_mfma_f32_16x16x32_bf16 v[104:107], v[188:191], v[220:223], v[104:107]
	v_mfma_f32_16x16x32_bf16 v[92:95], v[158:161], v[228:231], v[92:95]
	v_mfma_f32_16x16x32_bf16 v[88:91], v[188:191], v[228:231], v[88:91]
	v_mfma_f32_16x16x32_bf16 v[76:79], v[158:161], v[236:239], v[76:79]
	v_mfma_f32_16x16x32_bf16 v[72:75], v[188:191], v[236:239], v[72:75]
	s_setprio 0
	s_setprio 1
	v_mfma_f32_16x16x32_bf16 v[116:119], v[192:195], v[208:211], v[116:119]
	v_mfma_f32_16x16x32_bf16 v[112:115], v[200:203], v[208:211], v[112:115]
	v_mfma_f32_16x16x32_bf16 v[100:103], v[192:195], v[216:219], v[100:103]
	v_mfma_f32_16x16x32_bf16 v[96:99], v[200:203], v[216:219], v[96:99]
	v_mfma_f32_16x16x32_bf16 v[84:87], v[192:195], v[224:227], v[84:87]
	v_mfma_f32_16x16x32_bf16 v[80:83], v[200:203], v[224:227], v[80:83]
	v_mfma_f32_16x16x32_bf16 v[68:71], v[192:195], v[232:235], v[68:71]
	v_mfma_f32_16x16x32_bf16 v[64:67], v[200:203], v[232:235], v[64:67]
	v_mfma_f32_16x16x32_bf16 v[116:119], v[196:199], v[212:215], v[116:119]
	v_mfma_f32_16x16x32_bf16 v[112:115], v[204:207], v[212:215], v[112:115]
	v_mfma_f32_16x16x32_bf16 v[100:103], v[196:199], v[220:223], v[100:103]
	v_mfma_f32_16x16x32_bf16 v[96:99], v[204:207], v[220:223], v[96:99]
	v_mfma_f32_16x16x32_bf16 v[84:87], v[196:199], v[228:231], v[84:87]
	v_mfma_f32_16x16x32_bf16 v[80:83], v[204:207], v[228:231], v[80:83]
	v_mfma_f32_16x16x32_bf16 v[68:71], v[196:199], v[236:239], v[68:71]
	v_mfma_f32_16x16x32_bf16 v[64:67], v[204:207], v[236:239], v[64:67]
	s_setprio 0
	s_barrier
; #define PG8_STAGE(bufoff, gbase, voff) do { _Pragma("unroll") for (int _i = 0; _i < 2; ++_i) \
;         __builtin_amdgcn_global_load_lds((const unsigned*)((const char*)(gbase) + (voff)[_i]), (PG8_LAS unsigned*)(lds + (bufoff) + ldsw + _i * 8192), 16, 0, 0); } while (0)
; #define PG8_LDA(dst, b, h) do { _Pragma("unroll") for (int m = 0; m < 4; ++m) _Pragma("unroll") for (int k = 0; k < 2; ++k) dst[m][k] = *(const PG8_LAS bf16x8*)(lds + PG8_SA(b, h) + aoff + m * 2048 + k * 1024); } while (0)
; #define PG8_MMA(ai, bj, At, Bt) do { __builtin_amdgcn_s_setprio(1); _Pragma("unroll") for (int m = 0; m < 4; ++m) _Pragma("unroll") for (int n = 0; n < 2; ++n) _Pragma("unroll") for (int k = 0; k < 2; ++k) \
;         acc[ai][bj][m][n] = __builtin_amdgcn_mfma_f32_16x16x32_bf16(Bt[n][k], At[m][k], acc[ai][bj][m][n], 0, 0, 0); __builtin_amdgcn_s_setprio(0); } while (0)
; #define PG8_WAIT_V(n) asm volatile("s_waitcnt vmcnt(" #n ")" ::: "memory")
; #define PG8_WAIT_L(n) asm volatile("s_waitcnt lgkmcnt(" #n ")" ::: "memory")
; #define PG8_BAR __builtin_amdgcn_s_barrier()
; #define PG8_SCHED __builtin_amdgcn_sched_barrier(0)
; template <class Epi, class Sched, bool ALIGN_EPI = false, bool SP2 = false>
; __device__ __forceinline__ void gemm_phase(PG8_LAS unsigned char* lds, const Gemm g, const Sched& S, const Epi& E, const int tid) {
;     ...
;         for (int t = 0; t < nt; t += 2) {
;     ...
;             PG8_LDA(At, 1, 1); PG8_STAGE(PG8_SB(1, 0), b3, voffB); PG8_STAGE(PG8_SB(1, 1), b3 + hstepB, voffB); PG8_STAGE(PG8_SA(1, 0), a3, voffA);
;             PG8_WAIT_V(8); PG8_WAIT_L(0); PG8_BAR; PG8_MMA(1, 0, At, B0); PG8_MMA(1, 1, At, B1); PG8_BAR; PG8_SCHED;
	s_add_i32 s22, s36, s68
	v_lshl_add_u64 v[166:167], v[166:167], 0, s[76:77]
	s_mov_b32 m0, s22
	ds_read_b128 v[208:211], v157 offset:49152
	ds_read_b128 v[212:215], v157 offset:50176
	ds_read_b128 v[216:219], v157 offset:51200
	ds_read_b128 v[220:223], v157 offset:52224
	ds_read_b128 v[224:227], v157 offset:53248
	ds_read_b128 v[228:231], v157 offset:54272
	ds_read_b128 v[232:235], v157 offset:55296
	ds_read_b128 v[236:239], v157 offset:56320
	s_waitcnt vmcnt(2)
	s_waitcnt lgkmcnt(0)
	s_barrier
	s_setprio 1
	s_waitcnt lgkmcnt(0)
	v_mfma_f32_16x16x32_bf16 v[60:63], v[148:151], v[208:211], v[60:63]
	v_mfma_f32_16x16x32_bf16 v[56:59], v[162:165], v[208:211], v[56:59]
	global_load_lds_dwordx4 v[166:167], off
	v_mfma_f32_16x16x32_bf16 v[44:47], v[148:151], v[216:219], v[44:47]
	v_mfma_f32_16x16x32_bf16 v[40:43], v[162:165], v[216:219], v[40:43]
	v_mfma_f32_16x16x32_bf16 v[28:31], v[148:151], v[224:227], v[28:31]
	v_mfma_f32_16x16x32_bf16 v[24:27], v[162:165], v[224:227], v[24:27]
	v_mfma_f32_16x16x32_bf16 v[12:15], v[148:151], v[232:235], v[12:15]
	s_add_i32 m0, s22, 0x2000
	s_add_u32 s18, s18, 0x40080
	v_lshl_add_u64 v[166:167], v[240:241], 0, s[76:77]
	s_addc_u32 s19, s19, 0
	s_add_i32 s22, s37, s68
	global_load_lds_dwordx4 v[166:167], off
	v_mfma_f32_16x16x32_bf16 v[8:11], v[162:165], v[232:235], v[8:11]
	v_mfma_f32_16x16x32_bf16 v[60:63], v[158:161], v[212:215], v[60:63]
	v_mfma_f32_16x16x32_bf16 v[56:59], v[188:191], v[212:215], v[56:59]
	v_mfma_f32_16x16x32_bf16 v[44:47], v[158:161], v[220:223], v[44:47]
	v_mfma_f32_16x16x32_bf16 v[40:43], v[188:191], v[220:223], v[40:43]
	v_lshl_add_u64 v[166:167], s[18:19], 0, v[140:141]
	s_mov_b32 m0, s22
	s_nop 0
	global_load_lds_dwordx4 v[166:167], off
	v_mfma_f32_16x16x32_bf16 v[28:31], v[158:161], v[228:231], v[28:31]
	v_mfma_f32_16x16x32_bf16 v[24:27], v[188:191], v[228:231], v[24:27]
	v_mfma_f32_16x16x32_bf16 v[12:15], v[158:161], v[236:239], v[12:15]
	v_mfma_f32_16x16x32_bf16 v[8:11], v[188:191], v[236:239], v[8:11]
	s_setprio 0
	s_setprio 1
	v_mfma_f32_16x16x32_bf16 v[52:55], v[192:195], v[208:211], v[52:55]
	v_lshl_add_u64 v[166:167], s[18:19], 0, v[136:137]
	s_add_i32 m0, s22, 0x2000
	s_nop 0
	global_load_lds_dwordx4 v[166:167], off
	v_mfma_f32_16x16x32_bf16 v[48:51], v[200:203], v[208:211], v[48:51]
	v_mfma_f32_16x16x32_bf16 v[36:39], v[192:195], v[216:219], v[36:39]
	v_mfma_f32_16x16x32_bf16 v[32:35], v[200:203], v[216:219], v[32:35]
	v_mfma_f32_16x16x32_bf16 v[20:23], v[192:195], v[224:227], v[20:23]
	v_mfma_f32_16x16x32_bf16 v[16:19], v[200:203], v[224:227], v[16:19]
	v_lshl_add_u64 v[166:167], v[242:243], 0, s[76:77]
	s_mov_b32 m0, s84
	s_nop 0
	global_load_lds_dwordx4 v[166:167], off
	v_mfma_f32_16x16x32_bf16 v[4:7], v[192:195], v[232:235], v[4:7]
	v_mfma_f32_16x16x32_bf16 v[0:3], v[200:203], v[232:235], v[0:3]
	v_mfma_f32_16x16x32_bf16 v[52:55], v[196:199], v[212:215], v[52:55]
	v_mfma_f32_16x16x32_bf16 v[48:51], v[204:207], v[212:215], v[48:51]
	v_mfma_f32_16x16x32_bf16 v[36:39], v[196:199], v[220:223], v[36:39]
	v_lshl_add_u64 v[166:167], v[244:245], 0, s[76:77]
	s_mov_b32 m0, s87
	s_nop 0
	global_load_lds_dwordx4 v[166:167], off
	v_mfma_f32_16x16x32_bf16 v[32:35], v[204:207], v[220:223], v[32:35]
	v_mfma_f32_16x16x32_bf16 v[20:23], v[196:199], v[228:231], v[20:23]
	v_mfma_f32_16x16x32_bf16 v[16:19], v[204:207], v[228:231], v[16:19]
	v_mfma_f32_16x16x32_bf16 v[4:7], v[196:199], v[236:239], v[4:7]
	v_mfma_f32_16x16x32_bf16 v[0:3], v[204:207], v[236:239], v[0:3]
	s_setprio 0
	s_barrier
	s_add_i32 s31, s31, 2
	s_add_u32 s8, s8, 0x100
	s_addc_u32 s9, s9, 0
	s_add_u32 s29, s29, 0x100
	s_addc_u32 s30, s30, 0
	s_cmp_gt_u32 s31, 13
	s_cbranch_scc0 .LBB0_35
	s_and_b64 vcc, exec, s[10:11]
	s_cbranch_vccz .LBB0_38
	s_barrier

; #define PG8_STAGE(bufoff, gbase, voff) do { _Pragma("unroll") for (int _i = 0; _i < 2; ++_i) \
;         __builtin_amdgcn_global_load_lds((const unsigned*)((const char*)(gbase) + (voff)[_i]), (PG8_LAS unsigned*)(lds + (bufoff) + ldsw + _i * 8192), 16, 0, 0); } while (0)
; #define PG8_LDA(dst, b, h) do { _Pragma("unroll") for (int m = 0; m < 4; ++m) _Pragma("unroll") for (int k = 0; k < 2; ++k) dst[m][k] = *(const PG8_LAS bf16x8*)(lds + PG8_SA(b, h) + aoff + m * 2048 + k * 1024); } while (0)
; #define PG8_MMA(ai, bj, At, Bt) do { __builtin_amdgcn_s_setprio(1); _Pragma("unroll") for (int m = 0; m < 4; ++m) _Pragma("unroll") for (int n = 0; n < 2; ++n) _Pragma("unroll") for (int k = 0; k < 2; ++k) \
;         acc[ai][bj][m][n] = __builtin_amdgcn_mfma_f32_16x16x32_bf16(Bt[n][k], At[m][k], acc[ai][bj][m][n], 0, 0, 0); __builtin_amdgcn_s_setprio(0); } while (0)
; #define PG8_WAIT_V(n) asm volatile("s_waitcnt vmcnt(" #n ")" ::: "memory")
; #define PG8_WAIT_L(n) asm volatile("s_waitcnt lgkmcnt(" #n ")" ::: "memory")
; #define PG8_BAR __builtin_amdgcn_s_barrier()
; #define PG8_SCHED __builtin_amdgcn_sched_barrier(0)
; template <class Epi, class Sched, bool ALIGN_EPI = false, bool SP2 = false>
; __device__ __forceinline__ void gemm_phase(PG8_LAS unsigned char* lds, const Gemm g, const Sched& S, const Epi& E, const int tid) {
;     ...
;             PG8_WAIT_V(8); PG8_WAIT_L(0); PG8_BAR; PG8_MMA(0, 0, At, B0); PG8_MMA(0, 1, At, B1); PG8_BAR; PG8_SCHED;
;             PG8_LDA(At, 0, 1); PG8_STAGE(PG8_SB(0, 0), b2, voffB); PG8_STAGE(PG8_SB(0, 1), b2 + hstepB, voffB); PG8_STAGE(PG8_SA(0, 0), a2, voffA);
;             PG8_WAIT_V(8); PG8_WAIT_L(0); PG8_BAR; PG8_MMA(1, 0, At, B0); PG8_MMA(1, 1, At, B1); PG8_BAR; PG8_SCHED;
.Lkw_pl_0:
	s_waitcnt lgkmcnt(0)
	s_barrier
	s_setprio 1
	s_waitcnt lgkmcnt(0)
	v_mfma_f32_16x16x32_bf16 v[124:127], v[148:151], v[208:211], v[124:127]
	v_mfma_f32_16x16x32_bf16 v[120:123], v[162:165], v[208:211], v[120:123]
	v_mfma_f32_16x16x32_bf16 v[108:111], v[148:151], v[216:219], v[108:111]
	v_mfma_f32_16x16x32_bf16 v[104:107], v[162:165], v[216:219], v[104:107]
	v_mfma_f32_16x16x32_bf16 v[92:95], v[148:151], v[224:227], v[92:95]
	v_mfma_f32_16x16x32_bf16 v[88:91], v[162:165], v[224:227], v[88:91]
	v_mfma_f32_16x16x32_bf16 v[76:79], v[148:151], v[232:235], v[76:79]
	v_mfma_f32_16x16x32_bf16 v[72:75], v[162:165], v[232:235], v[72:75]
	v_mfma_f32_16x16x32_bf16 v[124:127], v[158:161], v[212:215], v[124:127]
	v_mfma_f32_16x16x32_bf16 v[120:123], v[188:191], v[212:215], v[120:123]
	v_mfma_f32_16x16x32_bf16 v[108:111], v[158:161], v[220:223], v[108:111]
	v_mfma_f32_16x16x32_bf16 v[104:107], v[188:191], v[220:223], v[104:107]
	v_mfma_f32_16x16x32_bf16 v[92:95], v[158:161], v[228:231], v[92:95]
	v_mfma_f32_16x16x32_bf16 v[88:91], v[188:191], v[228:231], v[88:91]
	v_mfma_f32_16x16x32_bf16 v[76:79], v[158:161], v[236:239], v[76:79]
	v_mfma_f32_16x16x32_bf16 v[72:75], v[188:191], v[236:239], v[72:75]
	s_setprio 0
	s_setprio 1
	v_mfma_f32_16x16x32_bf16 v[116:119], v[192:195], v[208:211], v[116:119]
	v_mfma_f32_16x16x32_bf16 v[112:115], v[200:203], v[208:211], v[112:115]
	v_mfma_f32_16x16x32_bf16 v[100:103], v[192:195], v[216:219], v[100:103]
	v_mfma_f32_16x16x32_bf16 v[96:99], v[200:203], v[216:219], v[96:99]
	v_mfma_f32_16x16x32_bf16 v[84:87], v[192:195], v[224:227], v[84:87]
	v_mfma_f32_16x16x32_bf16 v[80:83], v[200:203], v[224:227], v[80:83]
	v_mfma_f32_16x16x32_bf16 v[68:71], v[192:195], v[232:235], v[68:71]
	v_mfma_f32_16x16x32_bf16 v[64:67], v[200:203], v[232:235], v[64:67]
	v_mfma_f32_16x16x32_bf16 v[116:119], v[196:199], v[212:215], v[116:119]
	v_mfma_f32_16x16x32_bf16 v[112:115], v[204:207], v[212:215], v[112:115]
	v_mfma_f32_16x16x32_bf16 v[100:103], v[196:199], v[220:223], v[100:103]
	v_mfma_f32_16x16x32_bf16 v[96:99], v[204:207], v[220:223], v[96:99]
	v_mfma_f32_16x16x32_bf16 v[84:87], v[196:199], v[228:231], v[84:87]
	v_mfma_f32_16x16x32_bf16 v[80:83], v[204:207], v[228:231], v[80:83]
	v_mfma_f32_16x16x32_bf16 v[68:71], v[196:199], v[236:239], v[68:71]
	v_mfma_f32_16x16x32_bf16 v[64:67], v[204:207], v[236:239], v[64:67]
	s_setprio 0
	s_barrier
	s_add_i32 s50, s50, s81
	v_lshl_add_u64 v[166:167], s[48:49], 0, v[138:139]
	s_mov_b32 m0, s50
	ds_read_b128 v[208:211], v157 offset:16384
	ds_read_b128 v[212:215], v157 offset:17408
	ds_read_b128 v[216:219], v157 offset:18432
	ds_read_b128 v[220:223], v157 offset:19456
	ds_read_b128 v[224:227], v157 offset:20480
	ds_read_b128 v[228:231], v157 offset:21504
	ds_read_b128 v[232:235], v157 offset:22528
	ds_read_b128 v[236:239], v157 offset:23552
	s_cmp_eq_u32 s99, 1
	s_cbranch_scc1 .Lkw_pl_1
	s_waitcnt vmcnt(2)
.Lkw_pl_1:
	s_waitcnt lgkmcnt(0)
	s_barrier
	s_setprio 1
	s_waitcnt lgkmcnt(0)
	v_mfma_f32_16x16x32_bf16 v[60:63], v[148:151], v[208:211], v[60:63]
	v_mfma_f32_16x16x32_bf16 v[56:59], v[162:165], v[208:211], v[56:59]
	global_load_lds_dwordx4 v[166:167], off
	v_mfma_f32_16x16x32_bf16 v[44:47], v[148:151], v[216:219], v[44:47]
	v_mfma_f32_16x16x32_bf16 v[40:43], v[162:165], v[216:219], v[40:43]
	v_mfma_f32_16x16x32_bf16 v[28:31], v[148:151], v[224:227], v[28:31]
	v_mfma_f32_16x16x32_bf16 v[24:27], v[162:165], v[224:227], v[24:27]
	v_mfma_f32_16x16x32_bf16 v[12:15], v[148:151], v[232:235], v[12:15]
	s_add_i32 m0, s50, 0x2000
	v_lshl_add_u64 v[240:241], s[48:49], 0, v[142:143]
	s_add_u32 s48, s48, s21
	s_addc_u32 s49, s49, 0
	s_add_i32 s46, s46, s81
	global_load_lds_dwordx4 v[240:241], off
	v_mfma_f32_16x16x32_bf16 v[8:11], v[162:165], v[232:235], v[8:11]
	v_mfma_f32_16x16x32_bf16 v[60:63], v[158:161], v[212:215], v[60:63]
	v_mfma_f32_16x16x32_bf16 v[56:59], v[188:191], v[212:215], v[56:59]
	v_mfma_f32_16x16x32_bf16 v[44:47], v[158:161], v[220:223], v[44:47]
	v_mfma_f32_16x16x32_bf16 v[40:43], v[188:191], v[220:223], v[40:43]
	v_lshl_add_u64 v[242:243], s[48:49], 0, v[138:139]
	s_mov_b32 m0, s46
	v_lshl_add_u64 v[244:245], s[48:49], 0, v[142:143]
	global_load_lds_dwordx4 v[242:243], off
	v_mfma_f32_16x16x32_bf16 v[28:31], v[158:161], v[228:231], v[28:31]
	v_mfma_f32_16x16x32_bf16 v[24:27], v[188:191], v[228:231], v[24:27]
	v_mfma_f32_16x16x32_bf16 v[12:15], v[158:161], v[236:239], v[12:15]
	v_mfma_f32_16x16x32_bf16 v[8:11], v[188:191], v[236:239], v[8:11]
	s_setprio 0
	s_setprio 1
	v_mfma_f32_16x16x32_bf16 v[52:55], v[192:195], v[208:211], v[52:55]
	s_add_i32 m0, s46, 0x2000
	v_lshl_add_u64 v[246:247], s[92:93], 0, v[136:137]
	global_load_lds_dwordx4 v[244:245], off
	v_mfma_f32_16x16x32_bf16 v[48:51], v[200:203], v[208:211], v[48:51]
	v_mfma_f32_16x16x32_bf16 v[36:39], v[192:195], v[216:219], v[36:39]
	v_mfma_f32_16x16x32_bf16 v[32:35], v[200:203], v[216:219], v[32:35]
	v_mfma_f32_16x16x32_bf16 v[20:23], v[192:195], v[224:227], v[20:23]
	v_mfma_f32_16x16x32_bf16 v[16:19], v[200:203], v[224:227], v[16:19]
	s_mov_b32 m0, s72
	v_lshl_add_u64 v[248:249], s[92:93], 0, v[140:141]
	global_load_lds_dwordx4 v[246:247], off
	v_mfma_f32_16x16x32_bf16 v[4:7], v[192:195], v[232:235], v[4:7]
	v_mfma_f32_16x16x32_bf16 v[0:3], v[200:203], v[232:235], v[0:3]
	v_mfma_f32_16x16x32_bf16 v[52:55], v[196:199], v[212:215], v[52:55]
	v_mfma_f32_16x16x32_bf16 v[48:51], v[204:207], v[212:215], v[48:51]
	v_mfma_f32_16x16x32_bf16 v[36:39], v[196:199], v[220:223], v[36:39]
	s_mov_b32 m0, s73
	s_nop 0
	global_load_lds_dwordx4 v[248:249], off
	v_mfma_f32_16x16x32_bf16 v[32:35], v[204:207], v[220:223], v[32:35]
	v_mfma_f32_16x16x32_bf16 v[20:23], v[196:199], v[228:231], v[20:23]
	v_mfma_f32_16x16x32_bf16 v[16:19], v[204:207], v[228:231], v[16:19]
	v_mfma_f32_16x16x32_bf16 v[4:7], v[196:199], v[236:239], v[4:7]
	v_mfma_f32_16x16x32_bf16 v[0:3], v[204:207], v[236:239], v[0:3]
	s_setprio 0
	s_barrier
; #define PG8_STAGE(bufoff, gbase, voff) do { _Pragma("unroll") for (int _i = 0; _i < 2; ++_i) \
;         __builtin_amdgcn_global_load_lds((const unsigned*)((const char*)(gbase) + (voff)[_i]), (PG8_LAS unsigned*)(lds + (bufoff) + ldsw + _i * 8192), 16, 0, 0); } while (0)
; #define PG8_LDA(dst, b, h) do { _Pragma("unroll") for (int m = 0; m < 4; ++m) _Pragma("unroll") for (int k = 0; k < 2; ++k) dst[m][k] = *(const PG8_LAS bf16x8*)(lds + PG8_SA(b, h) + aoff + m * 2048 + k * 1024); } while (0)
; #define PG8_LDB(dst, b, h) do { _Pragma("unroll") for (int n = 0; n < 2; ++n) _Pragma("unroll") for (int k = 0; k < 2; ++k) dst[n][k] = *(const PG8_LAS bf16x8*)(lds + PG8_SB(b, h) + boff + n * 2048 + k * 1024); } while (0)
; #define PG8_MMA(ai, bj, At, Bt) do { __builtin_amdgcn_s_setprio(1); _Pragma("unroll") for (int m = 0; m < 4; ++m) _Pragma("unroll") for (int n = 0; n < 2; ++n) _Pragma("unroll") for (int k = 0; k < 2; ++k) \
;         acc[ai][bj][m][n] = __builtin_amdgcn_mfma_f32_16x16x32_bf16(Bt[n][k], At[m][k], acc[ai][bj][m][n], 0, 0, 0); __builtin_amdgcn_s_setprio(0); } while (0)
; #define PG8_WAIT_V(n) asm volatile("s_waitcnt vmcnt(" #n ")" ::: "memory")
; #define PG8_WAIT_L(n) asm volatile("s_waitcnt lgkmcnt(" #n ")" ::: "memory")
; #define PG8_BAR __builtin_amdgcn_s_barrier()
; #define PG8_SCHED __builtin_amdgcn_sched_barrier(0)
; template <class Epi, class Sched, bool ALIGN_EPI = false, bool SP2 = false>
; __device__ __forceinline__ void gemm_phase(PG8_LAS unsigned char* lds, const Gemm g, const Sched& S, const Epi& E, const int tid) {
;     ...
;             PG8_LDB(B0, 1, 0); PG8_LDB(B1, 1, 1); PG8_SCHED; PG8_LDA(At, 1, 0); PG8_STAGE(PG8_SA(0, 1), a2 + hstepA, voffA);
;             PG8_WAIT_V(8); PG8_WAIT_L(0); PG8_BAR; PG8_MMA(0, 0, At, B0); PG8_MMA(0, 1, At, B1); PG8_BAR; PG8_SCHED;
	s_add_i32 s46, 0, 0x18000
	v_add_u32_e32 v128, s46, v155
	s_add_i32 s50, 0, 0x1c000
	ds_read_b128 v[148:151], v128
	ds_read_b128 v[158:161], v128 offset:1024
	ds_read_b128 v[162:165], v128 offset:2048
	ds_read_b128 v[188:191], v128 offset:3072
	v_add_u32_e32 v128, s50, v155
	ds_read_b128 v[192:195], v128
	ds_read_b128 v[196:199], v128 offset:1024
	ds_read_b128 v[200:203], v128 offset:2048
	ds_read_b128 v[204:207], v128 offset:3072
	s_add_u32 s48, s92, s84
	s_addc_u32 s49, s93, 0
	s_mov_b32 m0, s24
	v_lshl_add_u64 v[250:251], s[48:49], 0, v[136:137]
	ds_read_b128 v[208:211], v157 offset:32768
	ds_read_b128 v[212:215], v157 offset:33792
	ds_read_b128 v[216:219], v157 offset:34816
	ds_read_b128 v[220:223], v157 offset:35840
	ds_read_b128 v[224:227], v157 offset:36864
	ds_read_b128 v[228:231], v157 offset:37888
	ds_read_b128 v[232:235], v157 offset:38912
	ds_read_b128 v[236:239], v157 offset:39936
	global_load_lds_dwordx4 v[250:251], off
	v_lshl_add_u64 v[250:251], s[48:49], 0, v[140:141]
	s_mov_b32 m0, s25
	s_nop 0
	global_load_lds_dwordx4 v[250:251], off
	s_waitcnt vmcnt(8)
	s_waitcnt lgkmcnt(0)
	s_barrier
	s_setprio 1
	s_waitcnt lgkmcnt(0)
	v_mfma_f32_16x16x32_bf16 v[124:127], v[148:151], v[208:211], v[124:127]
	v_mfma_f32_16x16x32_bf16 v[120:123], v[162:165], v[208:211], v[120:123]
	v_mfma_f32_16x16x32_bf16 v[108:111], v[148:151], v[216:219], v[108:111]
	v_mfma_f32_16x16x32_bf16 v[104:107], v[162:165], v[216:219], v[104:107]
	v_mfma_f32_16x16x32_bf16 v[92:95], v[148:151], v[224:227], v[92:95]
	v_mfma_f32_16x16x32_bf16 v[88:91], v[162:165], v[224:227], v[88:91]
	v_mfma_f32_16x16x32_bf16 v[76:79], v[148:151], v[232:235], v[76:79]
	v_mfma_f32_16x16x32_bf16 v[72:75], v[162:165], v[232:235], v[72:75]
	v_mfma_f32_16x16x32_bf16 v[124:127], v[158:161], v[212:215], v[124:127]
	v_mfma_f32_16x16x32_bf16 v[120:123], v[188:191], v[212:215], v[120:123]
	v_mfma_f32_16x16x32_bf16 v[108:111], v[158:161], v[220:223], v[108:111]
	v_mfma_f32_16x16x32_bf16 v[104:107], v[188:191], v[220:223], v[104:107]
	v_mfma_f32_16x16x32_bf16 v[92:95], v[158:161], v[228:231], v[92:95]
	v_mfma_f32_16x16x32_bf16 v[88:91], v[188:191], v[228:231], v[88:91]
	v_mfma_f32_16x16x32_bf16 v[76:79], v[158:161], v[236:239], v[76:79]
	v_mfma_f32_16x16x32_bf16 v[72:75], v[188:191], v[236:239], v[72:75]
	s_setprio 0
	s_setprio 1
	v_mfma_f32_16x16x32_bf16 v[116:119], v[192:195], v[208:211], v[116:119]
	v_mfma_f32_16x16x32_bf16 v[112:115], v[200:203], v[208:211], v[112:115]
	v_mfma_f32_16x16x32_bf16 v[100:103], v[192:195], v[216:219], v[100:103]
	v_mfma_f32_16x16x32_bf16 v[96:99], v[200:203], v[216:219], v[96:99]
	v_mfma_f32_16x16x32_bf16 v[84:87], v[192:195], v[224:227], v[84:87]
	v_mfma_f32_16x16x32_bf16 v[80:83], v[200:203], v[224:227], v[80:83]
	v_mfma_f32_16x16x32_bf16 v[68:71], v[192:195], v[232:235], v[68:71]
	v_mfma_f32_16x16x32_bf16 v[64:67], v[200:203], v[232:235], v[64:67]
	v_mfma_f32_16x16x32_bf16 v[116:119], v[196:199], v[212:215], v[116:119]
	v_mfma_f32_16x16x32_bf16 v[112:115], v[204:207], v[212:215], v[112:115]
	v_mfma_f32_16x16x32_bf16 v[100:103], v[196:199], v[220:223], v[100:103]
	v_mfma_f32_16x16x32_bf16 v[96:99], v[204:207], v[220:223], v[96:99]
	v_mfma_f32_16x16x32_bf16 v[84:87], v[196:199], v[228:231], v[84:87]
	v_mfma_f32_16x16x32_bf16 v[80:83], v[204:207], v[228:231], v[80:83]
	v_mfma_f32_16x16x32_bf16 v[68:71], v[196:199], v[236:239], v[68:71]
	v_mfma_f32_16x16x32_bf16 v[64:67], v[204:207], v[236:239], v[64:67]
	s_setprio 0
	s_barrier
; #define PG8_STAGE(bufoff, gbase, voff) do { _Pragma("unroll") for (int _i = 0; _i < 2; ++_i) \
;         __builtin_amdgcn_global_load_lds((const unsigned*)((const char*)(gbase) + (voff)[_i]), (PG8_LAS unsigned*)(lds + (bufoff) + ldsw + _i * 8192), 16, 0, 0); } while (0)
; #define PG8_LDA(dst, b, h) do { _Pragma("unroll") for (int m = 0; m < 4; ++m) _Pragma("unroll") for (int k = 0; k < 2; ++k) dst[m][k] = *(const PG8_LAS bf16x8*)(lds + PG8_SA(b, h) + aoff + m * 2048 + k * 1024); } while (0)
; #define PG8_MMA(ai, bj, At, Bt) do { __builtin_amdgcn_s_setprio(1); _Pragma("unroll") for (int m = 0; m < 4; ++m) _Pragma("unroll") for (int n = 0; n < 2; ++n) _Pragma("unroll") for (int k = 0; k < 2; ++k) \
;         acc[ai][bj][m][n] = __builtin_amdgcn_mfma_f32_16x16x32_bf16(Bt[n][k], At[m][k], acc[ai][bj][m][n], 0, 0, 0); __builtin_amdgcn_s_setprio(0); } while (0)
; #define PG8_WAIT_V(n) asm volatile("s_waitcnt vmcnt(" #n ")" ::: "memory")
; #define PG8_WAIT_L(n) asm volatile("s_waitcnt lgkmcnt(" #n ")" ::: "memory")
; #define PG8_BAR __builtin_amdgcn_s_barrier()
; #define PG8_SCHED __builtin_amdgcn_sched_barrier(0)
; template <class Epi, class Sched, bool ALIGN_EPI = false, bool SP2 = false>
; __device__ __forceinline__ void gemm_phase(PG8_LAS unsigned char* lds, const Gemm g, const Sched& S, const Epi& E, const int tid) {
;     ...
;         for (int t = 0; t < nt; t += 2) {
;     ...
;             PG8_LDA(At, 1, 1); PG8_STAGE(PG8_SB(1, 0), b3, voffB); PG8_STAGE(PG8_SB(1, 1), b3 + hstepB, voffB); PG8_STAGE(PG8_SA(1, 0), a3, voffA);
;             PG8_WAIT_V(8); PG8_WAIT_L(0); PG8_BAR; PG8_MMA(1, 0, At, B0); PG8_MMA(1, 1, At, B1); PG8_BAR; PG8_SCHED;
	s_add_i32 s46, s46, s81
	v_lshl_add_u64 v[166:167], v[166:167], 0, s[76:77]
	s_mov_b32 m0, s46
	ds_read_b128 v[208:211], v157 offset:49152
	ds_read_b128 v[212:215], v157 offset:50176
	ds_read_b128 v[216:219], v157 offset:51200
	ds_read_b128 v[220:223], v157 offset:52224
	ds_read_b128 v[224:227], v157 offset:53248
	ds_read_b128 v[228:231], v157 offset:54272
	ds_read_b128 v[232:235], v157 offset:55296
	ds_read_b128 v[236:239], v157 offset:56320
	s_waitcnt vmcnt(2)
	s_waitcnt lgkmcnt(0)
	s_barrier
	s_setprio 1
	s_waitcnt lgkmcnt(0)
	v_mfma_f32_16x16x32_bf16 v[60:63], v[148:151], v[208:211], v[60:63]
	v_mfma_f32_16x16x32_bf16 v[56:59], v[162:165], v[208:211], v[56:59]
	global_load_lds_dwordx4 v[166:167], off
	v_mfma_f32_16x16x32_bf16 v[44:47], v[148:151], v[216:219], v[44:47]
	v_mfma_f32_16x16x32_bf16 v[40:43], v[162:165], v[216:219], v[40:43]
	v_mfma_f32_16x16x32_bf16 v[28:31], v[148:151], v[224:227], v[28:31]
	v_mfma_f32_16x16x32_bf16 v[24:27], v[162:165], v[224:227], v[24:27]
	v_mfma_f32_16x16x32_bf16 v[12:15], v[148:151], v[232:235], v[12:15]
	v_lshl_add_u64 v[166:167], v[240:241], 0, s[76:77]
	s_add_i32 m0, s46, 0x2000
	s_add_i32 s46, s50, s81
	global_load_lds_dwordx4 v[166:167], off
	v_mfma_f32_16x16x32_bf16 v[8:11], v[162:165], v[232:235], v[8:11]
	v_mfma_f32_16x16x32_bf16 v[60:63], v[158:161], v[212:215], v[60:63]
	v_mfma_f32_16x16x32_bf16 v[56:59], v[188:191], v[212:215], v[56:59]
	v_mfma_f32_16x16x32_bf16 v[44:47], v[158:161], v[220:223], v[44:47]
	v_mfma_f32_16x16x32_bf16 v[40:43], v[188:191], v[220:223], v[40:43]
	v_lshl_add_u64 v[166:167], v[242:243], 0, s[76:77]
	s_mov_b32 m0, s46
	s_nop 0
	global_load_lds_dwordx4 v[166:167], off
	v_mfma_f32_16x16x32_bf16 v[28:31], v[158:161], v[228:231], v[28:31]
	v_mfma_f32_16x16x32_bf16 v[24:27], v[188:191], v[228:231], v[24:27]
	v_mfma_f32_16x16x32_bf16 v[12:15], v[158:161], v[236:239], v[12:15]
	v_mfma_f32_16x16x32_bf16 v[8:11], v[188:191], v[236:239], v[8:11]
	s_setprio 0
	s_setprio 1
	v_mfma_f32_16x16x32_bf16 v[52:55], v[192:195], v[208:211], v[52:55]
	v_lshl_add_u64 v[166:167], v[244:245], 0, s[76:77]
	s_add_i32 m0, s46, 0x2000
	s_nop 0
	global_load_lds_dwordx4 v[166:167], off
	v_mfma_f32_16x16x32_bf16 v[48:51], v[200:203], v[208:211], v[48:51]
	v_mfma_f32_16x16x32_bf16 v[36:39], v[192:195], v[216:219], v[36:39]
	v_mfma_f32_16x16x32_bf16 v[32:35], v[200:203], v[216:219], v[32:35]
	v_mfma_f32_16x16x32_bf16 v[20:23], v[192:195], v[224:227], v[20:23]
	v_mfma_f32_16x16x32_bf16 v[16:19], v[200:203], v[224:227], v[16:19]
	v_lshl_add_u64 v[166:167], v[246:247], 0, s[76:77]
	s_mov_b32 m0, s27
	s_nop 0
	global_load_lds_dwordx4 v[166:167], off
	v_mfma_f32_16x16x32_bf16 v[4:7], v[192:195], v[232:235], v[4:7]
	v_mfma_f32_16x16x32_bf16 v[0:3], v[200:203], v[232:235], v[0:3]
	v_mfma_f32_16x16x32_bf16 v[52:55], v[196:199], v[212:215], v[52:55]
	v_mfma_f32_16x16x32_bf16 v[48:51], v[204:207], v[212:215], v[48:51]
	v_mfma_f32_16x16x32_bf16 v[36:39], v[196:199], v[220:223], v[36:39]
	v_lshl_add_u64 v[166:167], v[248:249], 0, s[76:77]
	s_mov_b32 m0, s28
	s_nop 0
	global_load_lds_dwordx4 v[166:167], off
	v_mfma_f32_16x16x32_bf16 v[32:35], v[204:207], v[220:223], v[32:35]
	v_mfma_f32_16x16x32_bf16 v[20:23], v[196:199], v[228:231], v[20:23]
	v_mfma_f32_16x16x32_bf16 v[16:19], v[204:207], v[228:231], v[16:19]
	v_mfma_f32_16x16x32_bf16 v[4:7], v[196:199], v[236:239], v[4:7]
	v_mfma_f32_16x16x32_bf16 v[0:3], v[204:207], v[236:239], v[0:3]
	s_setprio 0
	s_barrier
	s_add_u32 s8, s8, 0x100
	s_addc_u32 s9, s9, 0
	s_add_u32 s44, s44, 0x100
	s_addc_u32 s45, s45, 0
	s_cmp_ge_u32 s47, s14
	s_mov_b32 s46, s47
	s_cbranch_scc0 .LBB0_468
	s_and_b64 vcc, exec, s[22:23]
	s_cbranch_vccz .LBB0_471
	s_barrier
